# v89 plus P7 kmean hi/lo LDS images use the 16-slot XOR swizzle (conflict-free ds_read_b128)
# baseline (speedup 1.0000x reference)
.LBB0_852:
	s_and_b64 vcc, exec, s[0:1]
	s_cbranch_vccnz .LBB0_882
	v_mov_b32_e32 v87, 0
	v_lshlrev_b32_e32 v86, 2, v198
	v_or_b32_e32 v93, s8, v198
	v_lshl_add_u64 v[4:5], s[38:39], 0, v[86:87]
	s_mov_b64 s[8:9], 0x10000
	v_or_b32_e32 v9, 0x200, v0
	v_lshrrev_b32_e32 v6, 5, v198
	v_lshl_add_u64 v[88:89], v[4:5], 0, s[8:9]
	v_lshrrev_b32_e32 v104, 4, v0
	v_lshlrev_b32_e32 v5, 4, v0
	v_lshrrev_b32_e32 v105, 4, v9
	v_lshlrev_b32_e32 v92, 2, v6
	v_lshlrev_b32_e32 v4, 8, v104
	v_and_b32_e32 v7, 0xf0, v5
	s_movk_i32 s8, 0xf0
	v_and_b32_e32 v8, 0xf0, v0
	v_lshlrev_b32_e32 v9, 8, v105
	v_lshlrev_b32_e32 v6, 4, v6
	v_bitop3_b32 v4, v7, v4, v8 bitop3:0xde
	v_bitop3_b32 v7, v9, v7, v8 bitop3:0xf6
	v_and_b32_e32 v8, 0xf0, v5
	v_bitop3_b32 v5, v6, v5, s8 bitop3:0x78
	s_movk_i32 s8, 0x60
	s_add_u32 s51, s38, 0x2200000
	v_bitop3_b32 v11, v6, v8, s8 bitop3:0x36
	s_movk_i32 s8, 0x80
	s_addc_u32 s52, s39, 0
	v_bitop3_b32 v12, v6, v8, s8 bitop3:0x36
	s_movk_i32 s8, 0xa0
	s_add_u32 s53, s38, 0x2000000
	v_bitop3_b32 v13, v6, v8, s8 bitop3:0x36
	s_movk_i32 s8, 0xc0
	s_addc_u32 s54, s39, 0
	v_bitop3_b32 v14, v6, v8, s8 bitop3:0x36
	s_movk_i32 s8, 0xe0
	v_lshl_add_u32 v3, v3, 8, 0
	v_bitop3_b32 v9, v6, v8, 32 bitop3:0x36
	v_bitop3_b32 v10, v6, v8, 64 bitop3:0x36
	v_bitop3_b32 v6, v6, v8, s8 bitop3:0x36
	s_cmp_lt_u32 s31, 64
	v_add_u32_e32 v114, 0, v86
	v_lshlrev_b32_e32 v86, 2, v2
	v_mbcnt_lo_u32_b32 v2, -1, 0
	s_mov_b32 s23, 0
	v_lshl_add_u32 v94, v0, 2, 0
	v_or_b32_e32 v95, 2, v92
	v_or_b32_e32 v96, 8, v92
	v_or_b32_e32 v97, 10, v92
	v_or_b32_e32 v98, 16, v92
	v_or_b32_e32 v99, 18, v92
	v_or_b32_e32 v100, 24, v92
	v_or_b32_e32 v101, 26, v92
	v_cmp_gt_u32_e64 s[0:1], 32, v198
	v_cmp_gt_u32_e64 s[4:5], 2, v198
	v_cmp_gt_u32_e64 s[6:7], 8, v198
	v_or_b32_e32 v102, 0x100, v93
	v_or_b32_e32 v103, 0x200, v93
	v_or_b32_e32 v106, 1, v92
	v_or_b32_e32 v107, 3, v92
	v_or_b32_e32 v108, 9, v92
	v_or_b32_e32 v109, 11, v92
	v_or_b32_e32 v110, 17, v92
	v_or_b32_e32 v111, 19, v92
	v_or_b32_e32 v112, 25, v92
	v_or_b32_e32 v113, 27, v92
	s_cselect_b64 s[24:25], -1, 0
	v_cmp_eq_u32_e64 s[8:9], 0, v198
	v_cmp_ne_u32_e64 s[10:11], 0, v198
	v_cmp_gt_u32_e64 s[12:13], 4, v198
	v_cmp_gt_u32_e64 s[14:15], 16, v198
	v_lshl_add_u64 v[90:91], s[18:19], 0, v[86:87]
	s_movk_i32 s55, 0x7fff
	v_add_u32_e32 v115, 0, v4
	v_add_u32_e32 v116, 0, v7
	v_add_u32_e32 v117, v3, v5
	v_add_u32_e32 v118, v3, v9
	v_add_u32_e32 v119, v3, v10
	v_add_u32_e32 v120, v3, v11
	v_add_u32_e32 v121, v3, v12
	v_add_u32_e32 v122, v3, v13
	v_add_u32_e32 v123, v3, v14
	v_add_u32_e32 v124, v3, v6
	s_mov_b64 s[26:27], 0x4000
	s_movk_i32 s56, 0x4000
	s_movk_i32 s57, 0xffc0
	v_mov_b32_e32 v125, 1
	v_mbcnt_hi_u32_b32 v126, -1, v2
	s_mov_b32 s58, s50
	s_branch .LBB0_855
